# out-proj epilogue: gate vector loaded once per half, vmcnt(0) store ladder removed (re-evaluation with paired timing)
# baseline (speedup 1.0000x reference)
; template <int TJ>
; DI void outproj_tile(const Params& p, int l, char* smem, int b, int trow0, int n0) {
;     ...
;     const float* gt = p.mod + ((size_t)l * 9 + (trow0 < SEQ ? b : 8)) * 3072 + 2048 + n0 + 64 * wf;
;     const float* xs = src_row(p, l, b, trow0 + 32 * TJ * wt) + n0 + 64 * wf;
;     float* xd = dst_row(p, b, trow0 + 32 * TJ * wt) + n0 + 64 * wf;
;     char* sb = smem + wave * 8192;
;     float4 xo[2][4 * TJ];
; #pragma unroll
;     for (int i = 0; i < 2; ++i)
; #pragma unroll
;         for (int it = 0; it < 4 * TJ; ++it) {
;             const int c = lane + 64 * it, row = c >> 3, f = 32 * i + 4 * ((c & 7) ^ (row & 7));
;             xo[i][it] = *(const float4*)(xs + (size_t)row * D + f);
;         }
; #pragma unroll
;     for (int i = 0; i < 2; ++i) {
; #pragma unroll
;         for (int j = 0; j < TJ; ++j)
; #pragma unroll
;             for (int q = 0; q < 4; ++q) {
;                 const int row = 32 * j + r, c16 = 2 * q + h;
;                 float4 y; y.x = acc[i][j][4 * q]; y.y = acc[i][j][4 * q + 1]; y.z = acc[i][j][4 * q + 2]; y.w = acc[i][j][4 * q + 3];
;                 *(float4*)(sb + row * 128 + ((c16 ^ (row & 7)) << 4)) = y;
;             }
.LBB0_18:
	global_load_dwordx2 v[70:71], v[70:71], off
	s_and_b64 s[6:7], s[6:7], exec
	s_cselect_b32 s6, s4, 8
	s_ashr_i32 s7, s6, 31
	s_mul_i32 s34, s60, 9
	s_add_u32 s6, s34, s6
	s_mul_hi_i32 s34, s60, 9
	s_addc_u32 s7, s34, s7
	s_mulk_i32 s7, 0x3000
	s_mul_hi_u32 s34, s6, 0x3000
	s_load_dwordx4 s[56:59], s[0:1], 0xa8
	v_lshlrev_b64 v[64:65], v64, s[4:5]
	s_add_i32 s34, s34, s7
	s_mulk_i32 s6, 0x3000
	s_waitcnt lgkmcnt(0)
	s_add_u32 s28, s28, s6
	v_lshlrev_b64 v[68:69], 12, v[68:69]
	s_addc_u32 s29, s29, s34
	s_lshl_b64 s[6:7], s[8:9], 2
	v_ashrrev_i32_e32 v67, 31, v66
	v_cndmask_b32_e64 v67, 0, v67, s[40:41]
	v_and_b32_e32 v120, 63, v116
	v_or_b32_e32 v117, 64, v120
	v_mov_b32_e32 v73, v193
	v_or_b32_e32 v118, 0x80, v120
	v_mov_b32_e32 v77, v193
	v_or_b32_e32 v119, 0xc0, v120
	v_or_b32_e32 v124, 0x100, v120
	v_or_b32_e32 v125, 0x140, v120
	v_lshlrev_b32_e32 v122, 7, v116
	v_and_b32_e32 v123, 0xffffe000, v122
	v_or_b32_e32 v153, 0x180, v120
	v_or_b32_e32 v160, 0x1c0, v120
	v_bfe_u32 v121, v116, 5, 1
	v_lshrrev_b32_e32 v104, 3, v160
	v_add_u32_e32 v161, 32, v123
	v_and_b32_e32 v122, 0xf80, v122
	v_xor_b32_e32 v110, v104, v116
	v_add_u32_e32 v122, v161, v122
	v_and_b32_e32 v123, 7, v116
	s_add_u32 s8, s28, s6
	v_mov_b32_e32 v87, v193
	v_mov_b32_e32 v89, v193
	s_addc_u32 s9, s29, s7
	v_mov_b32_e32 v91, v193
	v_mov_b32_e32 v93, v193
	v_mov_b32_e32 v97, v193
	v_mov_b32_e32 v99, v193
	v_lshlrev_b32_e32 v104, 12, v104
	v_mov_b32_e32 v105, v193
	v_lshlrev_b32_e32 v110, 4, v110
	v_mov_b32_e32 v103, v193
	v_and_b32_e32 v110, 0x70, v110
	v_mov_b32_e32 v111, v193
	v_lshl_add_u32 v156, v124, 4, v161
	v_lshl_add_u32 v155, v125, 4, v161
	v_lshl_add_u32 v152, v120, 4, v161
	v_lshl_add_u32 v159, v117, 4, v161
	v_lshl_add_u32 v158, v118, 4, v161
	v_lshl_add_u32 v157, v119, 4, v161
	v_lshl_add_u32 v154, v153, 4, v161
	s_waitcnt vmcnt(0)
	v_lshl_add_u64 v[70:71], v[70:71], 0, v[64:65]
	v_and_b32_e32 v64, 64, v116
	v_lshl_add_u64 v[68:69], v[70:71], 0, v[68:69]
	v_lshlrev_b32_e32 v192, 2, v64
	v_lshl_add_u64 v[68:69], v[68:69], 0, s[6:7]
	v_lshl_add_u64 v[106:107], v[68:69], 0, v[192:193]
	v_add_u32_e32 v70, 0xfffff800, v66
	v_mov_b32_e32 v68, s59
	v_mov_b32_e32 v69, s57
	v_cndmask_b32_e64 v69, v68, v69, s[40:41]
	v_mov_b32_e32 v68, s58
	v_mov_b32_e32 v71, s56
	v_cndmask_b32_e64 v66, v70, v66, s[40:41]
	v_cndmask_b32_e64 v70, 20, 23, s[40:41]
	v_cndmask_b32_e64 v68, v68, v71, s[40:41]
	v_lshlrev_b64 v[70:71], v70, s[4:5]
	v_lshl_add_u64 v[68:69], v[68:69], 0, v[70:71]
	v_lshlrev_b64 v[66:67], 12, v[66:67]
	v_lshl_add_u64 v[66:67], v[68:69], 0, v[66:67]
	v_lshl_add_u64 v[114:115], v[66:67], 0, s[6:7]
	v_bfe_u32 v66, v116, 3, 3
	v_xor_b32_e32 v68, v66, v116
	v_lshlrev_b32_e32 v66, 12, v66
	v_mov_b32_e32 v67, v193
	v_lshlrev_b32_e32 v68, 4, v68
	v_lshl_add_u64 v[70:71], v[106:107], 0, v[66:67]
	v_and_b32_e32 v68, 0x70, v68
	v_mov_b32_e32 v69, v193
	v_lshl_add_u64 v[112:113], v[70:71], 0, v[68:69]
	v_lshrrev_b32_e32 v70, 3, v117
	v_xor_b32_e32 v72, v70, v116
	v_lshlrev_b32_e32 v70, 12, v70
	v_mov_b32_e32 v71, v193
	v_lshlrev_b32_e32 v72, 4, v72
	v_lshl_add_u64 v[74:75], v[106:107], 0, v[70:71]
	v_and_b32_e32 v72, 0x70, v72
	v_lshl_add_u64 v[108:109], v[74:75], 0, v[72:73]
	v_lshrrev_b32_e32 v74, 3, v118
	v_xor_b32_e32 v76, v74, v116
	v_lshlrev_b32_e32 v74, 12, v74
	v_mov_b32_e32 v75, v193
	v_lshlrev_b32_e32 v76, 4, v76
	v_lshl_add_u64 v[78:79], v[106:107], 0, v[74:75]
	v_and_b32_e32 v76, 0x70, v76
	v_lshl_add_u64 v[100:101], v[78:79], 0, v[76:77]
	v_lshrrev_b32_e32 v78, 3, v119
	v_xor_b32_e32 v82, v78, v116
	v_lshlrev_b32_e32 v82, 4, v82
	v_and_b32_e32 v86, 0x70, v82
	v_lshrrev_b32_e32 v82, 3, v124
	v_xor_b32_e32 v84, v82, v116
	v_lshlrev_b32_e32 v84, 4, v84
	v_and_b32_e32 v90, 0x70, v84
	v_lshrrev_b32_e32 v84, 3, v125
	v_xor_b32_e32 v94, v84, v116
	v_lshlrev_b32_e32 v94, 4, v94
	v_and_b32_e32 v96, 0x70, v94
	v_lshrrev_b32_e32 v94, 3, v153
	v_xor_b32_e32 v102, v94, v116
	v_bitop3_b32 v116, v121, v116, 7 bitop3:0x78
	v_lshl_add_u32 v148, v116, 4, v122
	ds_write_b128 v148, v[48:51]
	v_bitop3_b32 v48, v121, v123, 2 bitop3:0x36
	v_lshl_add_u32 v149, v48, 4, v122
	v_bitop3_b32 v48, v121, v123, 4 bitop3:0x36
	v_lshl_add_u32 v150, v48, 4, v122
	v_bitop3_b32 v48, v121, v123, 6 bitop3:0x36
	v_lshl_add_u64 v[114:115], v[114:115], 0, v[192:193]
	v_lshl_add_u32 v151, v48, 4, v122
	ds_write_b128 v149, v[52:55]
	ds_write_b128 v150, v[56:59]
	ds_write_b128 v151, v[60:63]
	ds_write_b128 v148, v[32:35] offset:4096
	ds_write_b128 v149, v[36:39] offset:4096
	ds_write_b128 v150, v[40:43] offset:4096
	ds_write_b128 v151, v[44:47] offset:4096
	v_lshl_add_u64 v[32:33], v[114:115], 0, v[66:67]
	v_lshl_add_u64 v[144:145], v[32:33], 0, v[68:69]
	v_lshl_add_u64 v[32:33], v[114:115], 0, v[70:71]
	v_lshlrev_b32_e32 v78, 12, v78
	v_mov_b32_e32 v79, v193
	v_lshl_add_u64 v[140:141], v[32:33], 0, v[72:73]
	v_lshl_add_u64 v[32:33], v[114:115], 0, v[74:75]
	v_lshlrev_b32_e32 v88, 12, v82
	v_lshl_add_u64 v[136:137], v[32:33], 0, v[76:77]
	v_lshl_add_u64 v[32:33], v[114:115], 0, v[78:79]
	v_lshlrev_b32_e32 v92, 12, v84
	v_lshl_add_u64 v[132:133], v[32:33], 0, v[86:87]
	v_lshl_add_u64 v[32:33], v[114:115], 0, v[88:89]
	v_lshl_add_u64 v[64:65], s[8:9], 0, v[192:193]
	v_lshlrev_b32_e32 v98, 12, v94
	v_lshlrev_b32_e32 v102, 4, v102
	v_lshl_add_u64 v[128:129], v[32:33], 0, v[90:91]
	v_lshl_add_u64 v[32:33], v[114:115], 0, v[92:93]
	v_lshl_add_u64 v[64:65], v[64:65], 0, s[16:17]
	v_lshl_add_u64 v[80:81], v[106:107], 0, v[78:79]
	v_lshl_add_u64 v[82:83], v[106:107], 0, v[88:89]
	v_lshl_add_u64 v[84:85], v[106:107], 0, v[92:93]
	v_lshl_add_u64 v[94:95], v[106:107], 0, v[98:99]
; template <int TJ>
; DI void outproj_tile(const Params& p, int l, char* smem, int b, int trow0, int n0) {
;     ...
; #pragma unroll
;         for (int it = 0; it < 4 * TJ; ++it) {
;             const int c = lane + 64 * it, row = c >> 3, f = 32 * i + 4 * ((c & 7) ^ (row & 7));
;             const float4 y = *(const float4*)(sb + c * 16);
;             const float4 g4 = *(const float4*)(gt + f);
;             float4 o;
;             o.x = xo[i][it].x + g4.x * y.x; o.y = xo[i][it].y + g4.y * y.y; o.z = xo[i][it].z + g4.z * y.z; o.w = xo[i][it].w + g4.w * y.w;
;             *(float4*)(xd + (size_t)row * D + f) = o;
;         }
;     }
	v_and_b32_e32 v102, 0x70, v102
	v_lshl_add_u64 v[106:107], v[106:107], 0, v[104:105]
	v_lshl_add_u64 v[124:125], v[32:33], 0, v[96:97]
	v_lshl_add_u64 v[32:33], v[114:115], 0, v[98:99]
	v_lshl_add_u64 v[80:81], v[80:81], 0, v[86:87]
	v_lshl_add_u64 v[82:83], v[82:83], 0, v[90:91]
	v_lshl_add_u64 v[84:85], v[84:85], 0, v[96:97]
	v_lshl_add_u64 v[94:95], v[94:95], 0, v[102:103]
	v_lshl_add_u64 v[106:107], v[106:107], 0, v[110:111]
	v_lshl_add_u64 v[146:147], v[64:65], 0, v[68:69]
	v_lshl_add_u64 v[120:121], v[32:33], 0, v[102:103]
	v_lshl_add_u64 v[32:33], v[114:115], 0, v[104:105]
	v_lshl_add_u64 v[142:143], v[64:65], 0, v[72:73]
	v_lshl_add_u64 v[138:139], v[64:65], 0, v[76:77]
	v_lshl_add_u64 v[134:135], v[64:65], 0, v[86:87]
	v_lshl_add_u64 v[130:131], v[64:65], 0, v[90:91]
	v_lshl_add_u64 v[126:127], v[64:65], 0, v[96:97]
	v_lshl_add_u64 v[122:123], v[64:65], 0, v[102:103]
	v_lshl_add_u64 v[118:119], v[64:65], 0, v[110:111]
	v_lshl_add_u64 v[116:117], v[32:33], 0, v[110:111]
	global_load_dwordx4 v[60:63], v[106:107], off
	global_load_dwordx4 v[32:35], v[106:107], off offset:128
	global_load_dwordx4 v[64:67], v[94:95], off
	global_load_dwordx4 v[36:39], v[94:95], off offset:128
	global_load_dwordx4 v[68:71], v[84:85], off
	global_load_dwordx4 v[40:43], v[84:85], off offset:128
	global_load_dwordx4 v[76:79], v[82:83], off
	global_load_dwordx4 v[44:47], v[82:83], off offset:128
	s_nop 0
	global_load_dwordx4 v[84:87], v[80:81], off
	ds_read_b128 v[88:91], v157
	global_load_dwordx4 v[48:51], v[80:81], off offset:128
	global_load_dwordx4 v[92:95], v[100:101], off
	ds_read_b128 v[96:99], v158
	ds_read_b128 v[80:83], v156
	global_load_dwordx4 v[52:55], v[100:101], off offset:128
	s_nop 0
	global_load_dwordx4 v[100:103], v[108:109], off
	ds_read_b128 v[104:107], v159
	ds_read_b128 v[72:75], v155
	global_load_dwordx4 v[56:59], v[108:109], off offset:128
	s_nop 0
	global_load_dwordx4 v[108:111], v[112:113], off
	global_load_dwordx4 v[164:167], v[146:147], off
	global_load_dwordx4 v[168:171], v[146:147], off offset:128
	v_lshl_add_u32 v153, v160, 4, v161
	ds_read_b128 v[160:163], v152
	global_load_dwordx4 v[112:115], v[112:113], off offset:128
	s_waitcnt vmcnt(0) lgkmcnt(0)
	v_pk_fma_f32 v[108:109], v[160:161], v[164:165], v[108:109]
	v_pk_fma_f32 v[110:111], v[162:163], v[166:167], v[110:111]
	global_store_dwordx4 v[144:145], v[108:111], off
	v_pk_fma_f32 v[100:101], v[104:105], v[164:165], v[100:101]
	v_pk_fma_f32 v[102:103], v[106:107], v[166:167], v[102:103]
	global_store_dwordx4 v[140:141], v[100:103], off
	v_pk_fma_f32 v[92:93], v[96:97], v[164:165], v[92:93]
	v_pk_fma_f32 v[94:95], v[98:99], v[166:167], v[94:95]
	global_store_dwordx4 v[136:137], v[92:95], off
	v_pk_fma_f32 v[84:85], v[88:89], v[164:165], v[84:85]
	v_pk_fma_f32 v[86:87], v[90:91], v[166:167], v[86:87]
	global_store_dwordx4 v[132:133], v[84:87], off
	v_pk_fma_f32 v[76:77], v[80:81], v[164:165], v[76:77]
	v_pk_fma_f32 v[78:79], v[82:83], v[166:167], v[78:79]
	global_store_dwordx4 v[128:129], v[76:79], off
	v_pk_fma_f32 v[68:69], v[72:73], v[164:165], v[68:69]
	v_pk_fma_f32 v[70:71], v[74:75], v[166:167], v[70:71]
	global_store_dwordx4 v[124:125], v[68:71], off
	s_nop 1
	ds_read_b128 v[68:71], v154
	s_waitcnt lgkmcnt(0)
	v_pk_fma_f32 v[64:65], v[68:69], v[164:165], v[64:65]
	v_pk_fma_f32 v[66:67], v[70:71], v[166:167], v[66:67]
	global_store_dwordx4 v[120:121], v[64:67], off
	s_nop 1
	ds_read_b128 v[64:67], v153
	s_waitcnt lgkmcnt(0)
	v_pk_fma_f32 v[60:61], v[64:65], v[164:165], v[60:61]
	v_pk_fma_f32 v[62:63], v[66:67], v[166:167], v[62:63]
	global_store_dwordx4 v[116:117], v[60:63], off
	ds_write_b128 v148, v[16:19]
	ds_write_b128 v149, v[20:23]
	ds_write_b128 v150, v[24:27]
	ds_write_b128 v151, v[28:31]
	ds_write_b128 v148, v[0:3] offset:4096
	ds_write_b128 v149, v[4:7] offset:4096
	ds_write_b128 v150, v[8:11] offset:4096
	ds_write_b128 v151, v[12:15] offset:4096
	ds_read_b128 v[0:3], v152
	s_waitcnt lgkmcnt(0)
	v_pk_fma_f32 v[0:1], v[0:1], v[168:169], v[112:113]
	v_pk_fma_f32 v[2:3], v[2:3], v[170:171], v[114:115]
	global_store_dwordx4 v[144:145], v[0:3], off offset:128
	s_nop 1
	ds_read_b128 v[0:3], v159
	s_waitcnt lgkmcnt(0)
	v_pk_fma_f32 v[0:1], v[0:1], v[168:169], v[56:57]
	v_pk_fma_f32 v[2:3], v[2:3], v[170:171], v[58:59]
	global_store_dwordx4 v[140:141], v[0:3], off offset:128
	s_nop 1
	ds_read_b128 v[0:3], v158
	s_waitcnt lgkmcnt(0)
	v_pk_fma_f32 v[0:1], v[0:1], v[168:169], v[52:53]
	v_pk_fma_f32 v[2:3], v[2:3], v[170:171], v[54:55]
	global_store_dwordx4 v[136:137], v[0:3], off offset:128
	s_nop 1
	ds_read_b128 v[0:3], v157
	s_waitcnt lgkmcnt(0)
	v_pk_fma_f32 v[0:1], v[0:1], v[168:169], v[48:49]
	v_pk_fma_f32 v[2:3], v[2:3], v[170:171], v[50:51]
	global_store_dwordx4 v[132:133], v[0:3], off offset:128
	s_nop 1
	ds_read_b128 v[0:3], v156
	s_waitcnt lgkmcnt(0)
	v_pk_fma_f32 v[0:1], v[0:1], v[168:169], v[44:45]
	v_pk_fma_f32 v[2:3], v[2:3], v[170:171], v[46:47]
	global_store_dwordx4 v[128:129], v[0:3], off offset:128
	s_nop 1
	ds_read_b128 v[0:3], v155
	s_waitcnt lgkmcnt(0)
	v_pk_fma_f32 v[0:1], v[0:1], v[168:169], v[40:41]
	v_pk_fma_f32 v[2:3], v[2:3], v[170:171], v[42:43]
	global_store_dwordx4 v[124:125], v[0:3], off offset:128
	s_nop 1
	ds_read_b128 v[0:3], v154
	s_waitcnt lgkmcnt(0)
	v_pk_fma_f32 v[0:1], v[0:1], v[168:169], v[36:37]
	v_pk_fma_f32 v[2:3], v[2:3], v[170:171], v[38:39]
	global_store_dwordx4 v[120:121], v[0:3], off offset:128
	s_nop 1
	ds_read_b128 v[0:3], v153
	s_waitcnt lgkmcnt(0)
	v_pk_fma_f32 v[0:1], v[0:1], v[168:169], v[32:33]
	v_pk_fma_f32 v[2:3], v[2:3], v[170:171], v[34:35]
	global_store_dwordx4 v[116:117], v[0:3], off offset:128
	s_nop 1
